# c41 + merge and out K-loops: counted lgkmcnt waits per A fragment (MFMAs start as soon as their own fragments land)
# speedup vs baseline: 1.0130x; 1.0130x over previous
; template <bool LOWREG = false>
; __device__ __forceinline__ void gemm_core(const bf16_t* __restrict__ A, int lda, const bf16_t* __restrict__ Bt, int ldb, int K, f32x4 (&acc)[8][4], unsigned char* smem, int tid) {
;     ...
; #pragma unroll
;         for (int ks = 0; ks < 2; ++ks) {
;             bf16x8 bfr[4];
;             const int co = ((ks * 4 + kq) ^ swz) * 16;
; #pragma unroll
;             for (int ni = 0; ni < 4; ++ni) bfr[ni] = *(const bf16x8*)(sb + boff + ni * 2048 + co);
; #pragma unroll
;             for (int mh = 0; mh < 2; ++mh) {
;                 bf16x8 af[4];
; #pragma unroll
;                 for (int mi = 0; mi < 4; ++mi) af[mi] = *(const bf16x8*)(sb + aoff + (mh * 4 + mi) * 2048 + co);
;                 if (more) G_ISSUE1(kt + 1, st ^ 1, ks * 2 + mh);
;                 __builtin_amdgcn_sched_barrier(0);
;                 __builtin_amdgcn_s_setprio(1);
; #pragma unroll
;                 for (int mi = 0; mi < 4; ++mi)
; #pragma unroll
;                     for (int ni = 0; ni < 4; ++ni) acc[mh * 4 + mi][ni] = __builtin_amdgcn_mfma_f32_16x16x32_bf16(bfr[ni], af[mi], acc[mh * 4 + mi][ni], 0, 0, 0);
;                 __builtin_amdgcn_s_setprio(0);
;                 __builtin_amdgcn_sched_barrier(0);
;             }
;         }
;         }
.LBB0_1101:
	s_and_b32 s19, s17, 0x10000
	s_add_i32 s20, s19, 0
	s_xor_b32 s19, s19, 0x10000
	v_add_u32_e32 v252, s20, v197
	v_add_u32_e32 v214, s20, v196
	s_add_i32 s19, s9, s19
	v_add_u32_e32 v230, v252, v179
	v_add_u32_e32 v218, v214, v179
	v_lshl_add_u64 v[250:251], v[180:181], 0, s[38:39]
	s_mov_b32 m0, s19
	ds_read_b128 v[198:201], v230 offset:32768
	ds_read_b128 v[202:205], v230 offset:34816
	ds_read_b128 v[206:209], v230 offset:36864
	ds_read_b128 v[230:233], v230 offset:38912
	ds_read_b128 v[234:237], v218
	ds_read_b128 v[238:241], v218 offset:2048
	ds_read_b128 v[242:245], v218 offset:4096
	ds_read_b128 v[246:249], v218 offset:6144
	global_load_lds_dwordx4 v[250:251], off
	v_lshl_add_u64 v[250:251], v[188:189], 0, s[38:39]
	s_add_i32 m0, s19, 0x8000
	s_add_i32 s18, s18, 1
	global_load_lds_dwordx4 v[250:251], off
	s_setprio 1
	s_waitcnt lgkmcnt(3)
	v_mfma_f32_16x16x32_bf16 v[126:129], v[198:201], v[234:237], v[126:129]
	v_mfma_f32_16x16x32_bf16 v[122:125], v[202:205], v[234:237], v[122:125]
	v_mfma_f32_16x16x32_bf16 v[118:121], v[206:209], v[234:237], v[118:121]
	v_mfma_f32_16x16x32_bf16 v[114:117], v[230:233], v[234:237], v[114:117]
	s_waitcnt lgkmcnt(2)
	v_mfma_f32_16x16x32_bf16 v[110:113], v[198:201], v[238:241], v[110:113]
	v_mfma_f32_16x16x32_bf16 v[106:109], v[202:205], v[238:241], v[106:109]
	v_mfma_f32_16x16x32_bf16 v[102:105], v[206:209], v[238:241], v[102:105]
	v_mfma_f32_16x16x32_bf16 v[98:101], v[230:233], v[238:241], v[98:101]
	s_waitcnt lgkmcnt(1)
	v_mfma_f32_16x16x32_bf16 v[94:97], v[198:201], v[242:245], v[94:97]
	v_mfma_f32_16x16x32_bf16 v[90:93], v[202:205], v[242:245], v[90:93]
	v_mfma_f32_16x16x32_bf16 v[86:89], v[206:209], v[242:245], v[86:89]
	v_mfma_f32_16x16x32_bf16 v[82:85], v[230:233], v[242:245], v[82:85]
	s_waitcnt lgkmcnt(0)
	v_mfma_f32_16x16x32_bf16 v[76:79], v[198:201], v[246:249], v[76:79]
	v_mfma_f32_16x16x32_bf16 v[72:75], v[202:205], v[246:249], v[72:75]
	v_mfma_f32_16x16x32_bf16 v[68:71], v[206:209], v[246:249], v[68:71]
	v_mfma_f32_16x16x32_bf16 v[64:67], v[230:233], v[246:249], v[64:67]
	s_setprio 0
	v_lshl_add_u64 v[250:251], v[182:183], 0, s[38:39]
	s_add_i32 m0, s19, 0x2000
	ds_read_b128 v[234:237], v218 offset:8192
	ds_read_b128 v[238:241], v218 offset:10240
	ds_read_b128 v[242:245], v218 offset:12288
	ds_read_b128 v[246:249], v218 offset:14336
	global_load_lds_dwordx4 v[250:251], off
	v_lshl_add_u64 v[250:251], v[190:191], 0, s[38:39]
	s_add_i32 m0, s19, 0xa000
	s_nop 0
	global_load_lds_dwordx4 v[250:251], off
	s_setprio 1
	s_waitcnt lgkmcnt(3)
	v_mfma_f32_16x16x32_bf16 v[60:63], v[198:201], v[234:237], v[60:63]
	v_mfma_f32_16x16x32_bf16 v[56:59], v[202:205], v[234:237], v[56:59]
	v_mfma_f32_16x16x32_bf16 v[52:55], v[206:209], v[234:237], v[52:55]
	v_mfma_f32_16x16x32_bf16 v[48:51], v[230:233], v[234:237], v[48:51]
	s_waitcnt lgkmcnt(2)
	v_mfma_f32_16x16x32_bf16 v[44:47], v[198:201], v[238:241], v[44:47]
	v_mfma_f32_16x16x32_bf16 v[40:43], v[202:205], v[238:241], v[40:43]
	v_mfma_f32_16x16x32_bf16 v[36:39], v[206:209], v[238:241], v[36:39]
	v_mfma_f32_16x16x32_bf16 v[32:35], v[230:233], v[238:241], v[32:35]
	s_waitcnt lgkmcnt(1)
	v_mfma_f32_16x16x32_bf16 v[28:31], v[198:201], v[242:245], v[28:31]
	v_mfma_f32_16x16x32_bf16 v[24:27], v[202:205], v[242:245], v[24:27]
	v_mfma_f32_16x16x32_bf16 v[20:23], v[206:209], v[242:245], v[20:23]
	v_mfma_f32_16x16x32_bf16 v[16:19], v[230:233], v[242:245], v[16:19]
	s_waitcnt lgkmcnt(0)
	v_mfma_f32_16x16x32_bf16 v[12:15], v[198:201], v[246:249], v[12:15]
	v_mfma_f32_16x16x32_bf16 v[8:11], v[202:205], v[246:249], v[8:11]
	v_mfma_f32_16x16x32_bf16 v[4:7], v[206:209], v[246:249], v[4:7]
	v_mfma_f32_16x16x32_bf16 v[0:3], v[230:233], v[246:249], v[0:3]
	s_setprio 0
	v_add_u32_e32 v218, v252, v80
	v_add_u32_e32 v214, v214, v80
	v_lshl_add_u64 v[250:251], v[184:185], 0, s[38:39]
	s_add_i32 m0, s19, 0x4000
	ds_read_b128 v[198:201], v218 offset:32768
	ds_read_b128 v[202:205], v218 offset:34816
	ds_read_b128 v[206:209], v218 offset:36864
	ds_read_b128 v[230:233], v218 offset:38912
	ds_read_b128 v[234:237], v214
	ds_read_b128 v[238:241], v214 offset:2048
	ds_read_b128 v[242:245], v214 offset:4096
	ds_read_b128 v[246:249], v214 offset:6144
	global_load_lds_dwordx4 v[250:251], off
	v_lshl_add_u64 v[250:251], v[192:193], 0, s[38:39]
	s_add_i32 m0, s19, 0xc000
	s_nop 0
	global_load_lds_dwordx4 v[250:251], off
	s_setprio 1
	s_waitcnt lgkmcnt(3)
	v_mfma_f32_16x16x32_bf16 v[126:129], v[198:201], v[234:237], v[126:129]
	v_mfma_f32_16x16x32_bf16 v[122:125], v[202:205], v[234:237], v[122:125]
	v_mfma_f32_16x16x32_bf16 v[118:121], v[206:209], v[234:237], v[118:121]
	v_mfma_f32_16x16x32_bf16 v[114:117], v[230:233], v[234:237], v[114:117]
	s_waitcnt lgkmcnt(2)
	v_mfma_f32_16x16x32_bf16 v[110:113], v[198:201], v[238:241], v[110:113]
	v_mfma_f32_16x16x32_bf16 v[106:109], v[202:205], v[238:241], v[106:109]
	v_mfma_f32_16x16x32_bf16 v[102:105], v[206:209], v[238:241], v[102:105]
	v_mfma_f32_16x16x32_bf16 v[98:101], v[230:233], v[238:241], v[98:101]
	s_waitcnt lgkmcnt(1)
	v_mfma_f32_16x16x32_bf16 v[94:97], v[198:201], v[242:245], v[94:97]
	v_mfma_f32_16x16x32_bf16 v[90:93], v[202:205], v[242:245], v[90:93]
	v_mfma_f32_16x16x32_bf16 v[86:89], v[206:209], v[242:245], v[86:89]
	v_mfma_f32_16x16x32_bf16 v[82:85], v[230:233], v[242:245], v[82:85]
	s_waitcnt lgkmcnt(0)
; template <bool LOWREG = false>
; __device__ __forceinline__ void gemm_core(const bf16_t* __restrict__ A, int lda, const bf16_t* __restrict__ Bt, int ldb, int K, f32x4 (&acc)[8][4], unsigned char* smem, int tid) {
;     ...
; #pragma unroll
;         for (int ks = 0; ks < 2; ++ks) {
;             bf16x8 bfr[4];
;             const int co = ((ks * 4 + kq) ^ swz) * 16;
; #pragma unroll
;             for (int ni = 0; ni < 4; ++ni) bfr[ni] = *(const bf16x8*)(sb + boff + ni * 2048 + co);
; #pragma unroll
;             for (int mh = 0; mh < 2; ++mh) {
;                 bf16x8 af[4];
; #pragma unroll
;                 for (int mi = 0; mi < 4; ++mi) af[mi] = *(const bf16x8*)(sb + aoff + (mh * 4 + mi) * 2048 + co);
;                 if (more) G_ISSUE1(kt + 1, st ^ 1, ks * 2 + mh);
;                 __builtin_amdgcn_sched_barrier(0);
;                 __builtin_amdgcn_s_setprio(1);
; #pragma unroll
;                 for (int mi = 0; mi < 4; ++mi)
; #pragma unroll
;                     for (int ni = 0; ni < 4; ++ni) acc[mh * 4 + mi][ni] = __builtin_amdgcn_mfma_f32_16x16x32_bf16(bfr[ni], af[mi], acc[mh * 4 + mi][ni], 0, 0, 0);
;                 __builtin_amdgcn_s_setprio(0);
;                 __builtin_amdgcn_sched_barrier(0);
;             }
;         }
;         }
;         asm volatile("s_waitcnt vmcnt(0)" ::: "memory");
;         __syncthreads();
	v_mfma_f32_16x16x32_bf16 v[76:79], v[198:201], v[246:249], v[76:79]
	v_mfma_f32_16x16x32_bf16 v[72:75], v[202:205], v[246:249], v[72:75]
	v_mfma_f32_16x16x32_bf16 v[68:71], v[206:209], v[246:249], v[68:71]
	v_mfma_f32_16x16x32_bf16 v[64:67], v[230:233], v[246:249], v[64:67]
	s_setprio 0
	v_lshl_add_u64 v[250:251], v[186:187], 0, s[38:39]
	s_add_i32 m0, s19, 0x6000
	ds_read_b128 v[234:237], v214 offset:8192
	ds_read_b128 v[238:241], v214 offset:10240
	ds_read_b128 v[242:245], v214 offset:12288
	ds_read_b128 v[246:249], v214 offset:14336
	global_load_lds_dwordx4 v[250:251], off
	v_lshl_add_u64 v[250:251], v[194:195], 0, s[38:39]
	s_add_i32 m0, s19, 0xe000
	s_nop 0
	global_load_lds_dwordx4 v[250:251], off
	s_setprio 1
	s_waitcnt lgkmcnt(3)
	v_mfma_f32_16x16x32_bf16 v[60:63], v[198:201], v[234:237], v[60:63]
	v_mfma_f32_16x16x32_bf16 v[56:59], v[202:205], v[234:237], v[56:59]
	v_mfma_f32_16x16x32_bf16 v[52:55], v[206:209], v[234:237], v[52:55]
	v_mfma_f32_16x16x32_bf16 v[48:51], v[230:233], v[234:237], v[48:51]
	s_waitcnt lgkmcnt(2)
	v_mfma_f32_16x16x32_bf16 v[44:47], v[198:201], v[238:241], v[44:47]
	v_mfma_f32_16x16x32_bf16 v[40:43], v[202:205], v[238:241], v[40:43]
	v_mfma_f32_16x16x32_bf16 v[36:39], v[206:209], v[238:241], v[36:39]
	v_mfma_f32_16x16x32_bf16 v[32:35], v[230:233], v[238:241], v[32:35]
	s_waitcnt lgkmcnt(1)
	v_mfma_f32_16x16x32_bf16 v[28:31], v[198:201], v[242:245], v[28:31]
	v_mfma_f32_16x16x32_bf16 v[24:27], v[202:205], v[242:245], v[24:27]
	v_mfma_f32_16x16x32_bf16 v[20:23], v[206:209], v[242:245], v[20:23]
	v_mfma_f32_16x16x32_bf16 v[16:19], v[230:233], v[242:245], v[16:19]
	s_waitcnt lgkmcnt(0)
	v_mfma_f32_16x16x32_bf16 v[12:15], v[198:201], v[246:249], v[12:15]
	v_mfma_f32_16x16x32_bf16 v[8:11], v[202:205], v[246:249], v[8:11]
	v_mfma_f32_16x16x32_bf16 v[4:7], v[206:209], v[246:249], v[4:7]
	v_mfma_f32_16x16x32_bf16 v[0:3], v[230:233], v[246:249], v[0:3]
	s_setprio 0
	s_add_i32 s17, s17, 0x10000
	s_waitcnt vmcnt(0)
	s_add_u32 s38, s38, 0x80
	s_addc_u32 s39, s39, 0
	s_cmp_eq_u32 s16, s18
	s_waitcnt vmcnt(0)
	s_barrier
	s_cbranch_scc0 .LBB0_1101
; template <bool LOWREG = false>
; __device__ __forceinline__ void gemm_core(const bf16_t* __restrict__ A, int lda, const bf16_t* __restrict__ Bt, int ldb, int K, f32x4 (&acc)[8][4], unsigned char* smem, int tid) {
;     ...
; #pragma unroll
;         for (int ks = 0; ks < 2; ++ks) {
;             bf16x8 bfr[4];
;             const int co = ((ks * 4 + kq) ^ swz) * 16;
; #pragma unroll
;             for (int ni = 0; ni < 4; ++ni) bfr[ni] = *(const bf16x8*)(sb + boff + ni * 2048 + co);
; #pragma unroll
;             for (int mh = 0; mh < 2; ++mh) {
;                 bf16x8 af[4];
; #pragma unroll
;                 for (int mi = 0; mi < 4; ++mi) af[mi] = *(const bf16x8*)(sb + aoff + (mh * 4 + mi) * 2048 + co);
;                 if (more) G_ISSUE1(kt + 1, st ^ 1, ks * 2 + mh);
;                 __builtin_amdgcn_sched_barrier(0);
;                 __builtin_amdgcn_s_setprio(1);
; #pragma unroll
;                 for (int mi = 0; mi < 4; ++mi)
; #pragma unroll
;                     for (int ni = 0; ni < 4; ++ni) acc[mh * 4 + mi][ni] = __builtin_amdgcn_mfma_f32_16x16x32_bf16(bfr[ni], af[mi], acc[mh * 4 + mi][ni], 0, 0, 0);
;                 __builtin_amdgcn_s_setprio(0);
;                 __builtin_amdgcn_sched_barrier(0);
;             }
;         }
;         }
; __device__ void merge_phase(const Params& p, int l, unsigned char* smem) {
;     ...
;             const int lane = tid & 63, w = tid >> 6, wm = w >> 2, wn = w & 3, idx = lane & 15, kq = lane >> 4;
; #pragma unroll
;             for (int mi = 0; mi < 8; ++mi) {
;                 const int row = m0 + wm * 128 + mi * 16 + idx;
;                 const float rs = (br == 2) ? rstd[row] : 1.f;
	s_lshl_b32 s9, s16, 16
	s_and_b32 s9, s9, 0x10000
	s_add_i32 s9, s9, 0
	v_add_u32_e32 v208, s9, v197
	v_add_u32_e32 v209, s9, v196
	v_add_u32_e32 v192, v208, v179
	v_add_u32_e32 v179, v209, v179
	ds_read_b128 v[180:183], v192 offset:32768
	ds_read_b128 v[184:187], v192 offset:34816
	ds_read_b128 v[188:191], v192 offset:36864
	ds_read_b128 v[192:195], v192 offset:38912
	ds_read_b128 v[196:199], v179
	ds_read_b128 v[200:203], v179 offset:2048
	ds_read_b128 v[204:207], v179 offset:4096
	ds_read_b128 v[230:233], v179 offset:6144
	s_setprio 1
	s_waitcnt lgkmcnt(3)
	v_mfma_f32_16x16x32_bf16 v[126:129], v[180:183], v[196:199], v[126:129]
	v_mfma_f32_16x16x32_bf16 v[122:125], v[184:187], v[196:199], v[122:125]
	v_mfma_f32_16x16x32_bf16 v[118:121], v[188:191], v[196:199], v[118:121]
	v_mfma_f32_16x16x32_bf16 v[114:117], v[192:195], v[196:199], v[114:117]
	s_waitcnt lgkmcnt(2)
	v_mfma_f32_16x16x32_bf16 v[110:113], v[180:183], v[200:203], v[110:113]
	v_mfma_f32_16x16x32_bf16 v[106:109], v[184:187], v[200:203], v[106:109]
	v_mfma_f32_16x16x32_bf16 v[102:105], v[188:191], v[200:203], v[102:105]
	v_mfma_f32_16x16x32_bf16 v[98:101], v[192:195], v[200:203], v[98:101]
	s_waitcnt lgkmcnt(1)
	v_mfma_f32_16x16x32_bf16 v[94:97], v[180:183], v[204:207], v[94:97]
	v_mfma_f32_16x16x32_bf16 v[90:93], v[184:187], v[204:207], v[90:93]
	v_mfma_f32_16x16x32_bf16 v[86:89], v[188:191], v[204:207], v[86:89]
	v_mfma_f32_16x16x32_bf16 v[82:85], v[192:195], v[204:207], v[82:85]
	s_waitcnt lgkmcnt(0)
	v_mfma_f32_16x16x32_bf16 v[76:79], v[180:183], v[230:233], v[76:79]
	v_mfma_f32_16x16x32_bf16 v[72:75], v[184:187], v[230:233], v[72:75]
	v_mfma_f32_16x16x32_bf16 v[68:71], v[188:191], v[230:233], v[68:71]
	v_mfma_f32_16x16x32_bf16 v[64:67], v[192:195], v[230:233], v[64:67]
	s_setprio 0
	ds_read_b128 v[196:199], v179 offset:8192
	ds_read_b128 v[200:203], v179 offset:10240
	ds_read_b128 v[204:207], v179 offset:12288
	ds_read_b128 v[230:233], v179 offset:14336
	s_setprio 1
	s_waitcnt lgkmcnt(3)
	v_mfma_f32_16x16x32_bf16 v[60:63], v[180:183], v[196:199], v[60:63]
	v_mfma_f32_16x16x32_bf16 v[56:59], v[184:187], v[196:199], v[56:59]
	v_mfma_f32_16x16x32_bf16 v[52:55], v[188:191], v[196:199], v[52:55]
	v_mfma_f32_16x16x32_bf16 v[48:51], v[192:195], v[196:199], v[48:51]
	s_waitcnt lgkmcnt(2)
	v_mfma_f32_16x16x32_bf16 v[44:47], v[180:183], v[200:203], v[44:47]
	v_mfma_f32_16x16x32_bf16 v[40:43], v[184:187], v[200:203], v[40:43]
	v_mfma_f32_16x16x32_bf16 v[36:39], v[188:191], v[200:203], v[36:39]
	v_mfma_f32_16x16x32_bf16 v[32:35], v[192:195], v[200:203], v[32:35]
	s_waitcnt lgkmcnt(1)
	v_mfma_f32_16x16x32_bf16 v[28:31], v[180:183], v[204:207], v[28:31]
	v_mfma_f32_16x16x32_bf16 v[24:27], v[184:187], v[204:207], v[24:27]
	v_mfma_f32_16x16x32_bf16 v[20:23], v[188:191], v[204:207], v[20:23]
	v_mfma_f32_16x16x32_bf16 v[16:19], v[192:195], v[204:207], v[16:19]
	s_waitcnt lgkmcnt(0)
	v_mfma_f32_16x16x32_bf16 v[12:15], v[180:183], v[230:233], v[12:15]
	v_mfma_f32_16x16x32_bf16 v[8:11], v[184:187], v[230:233], v[8:11]
	v_mfma_f32_16x16x32_bf16 v[4:7], v[188:191], v[230:233], v[4:7]
	v_mfma_f32_16x16x32_bf16 v[0:3], v[192:195], v[230:233], v[0:3]
	s_setprio 0
	v_add_u32_e32 v179, v208, v80
	v_add_u32_e32 v80, v209, v80
	ds_read_b128 v[180:183], v179 offset:32768
	ds_read_b128 v[184:187], v179 offset:34816
	ds_read_b128 v[188:191], v179 offset:36864
	ds_read_b128 v[192:195], v179 offset:38912
	ds_read_b128 v[196:199], v80
	ds_read_b128 v[200:203], v80 offset:2048
	ds_read_b128 v[204:207], v80 offset:4096
	ds_read_b128 v[230:233], v80 offset:6144
	s_setprio 1
	s_waitcnt lgkmcnt(3)
	v_mfma_f32_16x16x32_bf16 v[126:129], v[180:183], v[196:199], v[126:129]
	v_mfma_f32_16x16x32_bf16 v[122:125], v[184:187], v[196:199], v[122:125]
	v_mfma_f32_16x16x32_bf16 v[118:121], v[188:191], v[196:199], v[118:121]
	v_mfma_f32_16x16x32_bf16 v[114:117], v[192:195], v[196:199], v[114:117]
	s_waitcnt lgkmcnt(2)
	v_mfma_f32_16x16x32_bf16 v[110:113], v[180:183], v[200:203], v[110:113]
	v_mfma_f32_16x16x32_bf16 v[106:109], v[184:187], v[200:203], v[106:109]
	v_mfma_f32_16x16x32_bf16 v[102:105], v[188:191], v[200:203], v[102:105]
	v_mfma_f32_16x16x32_bf16 v[98:101], v[192:195], v[200:203], v[98:101]
	s_waitcnt lgkmcnt(1)
	v_mfma_f32_16x16x32_bf16 v[94:97], v[180:183], v[204:207], v[94:97]
	v_mfma_f32_16x16x32_bf16 v[90:93], v[184:187], v[204:207], v[90:93]
	v_mfma_f32_16x16x32_bf16 v[86:89], v[188:191], v[204:207], v[86:89]
	v_mfma_f32_16x16x32_bf16 v[82:85], v[192:195], v[204:207], v[82:85]
	s_waitcnt lgkmcnt(0)
	v_mfma_f32_16x16x32_bf16 v[76:79], v[180:183], v[230:233], v[76:79]
	v_mfma_f32_16x16x32_bf16 v[72:75], v[184:187], v[230:233], v[72:75]
	v_mfma_f32_16x16x32_bf16 v[68:71], v[188:191], v[230:233], v[68:71]
	v_mfma_f32_16x16x32_bf16 v[64:67], v[192:195], v[230:233], v[64:67]
	s_setprio 0
	ds_read_b128 v[196:199], v80 offset:8192
	ds_read_b128 v[200:203], v80 offset:10240
	ds_read_b128 v[204:207], v80 offset:12288
	ds_read_b128 v[230:233], v80 offset:14336
	s_setprio 1
	s_waitcnt lgkmcnt(3)
	v_mfma_f32_16x16x32_bf16 v[60:63], v[180:183], v[196:199], v[60:63]
	v_mfma_f32_16x16x32_bf16 v[56:59], v[184:187], v[196:199], v[56:59]
	v_mfma_f32_16x16x32_bf16 v[52:55], v[188:191], v[196:199], v[52:55]
	v_mfma_f32_16x16x32_bf16 v[48:51], v[192:195], v[196:199], v[48:51]
	s_waitcnt lgkmcnt(2)
	v_mfma_f32_16x16x32_bf16 v[44:47], v[180:183], v[200:203], v[44:47]
	v_mfma_f32_16x16x32_bf16 v[40:43], v[184:187], v[200:203], v[40:43]
	v_mfma_f32_16x16x32_bf16 v[36:39], v[188:191], v[200:203], v[36:39]
	v_mfma_f32_16x16x32_bf16 v[32:35], v[192:195], v[200:203], v[32:35]
	s_waitcnt lgkmcnt(1)
	v_mfma_f32_16x16x32_bf16 v[28:31], v[180:183], v[204:207], v[28:31]
	v_mfma_f32_16x16x32_bf16 v[24:27], v[184:187], v[204:207], v[24:27]
	v_mfma_f32_16x16x32_bf16 v[20:23], v[188:191], v[204:207], v[20:23]
	v_mfma_f32_16x16x32_bf16 v[16:19], v[192:195], v[204:207], v[16:19]
	s_waitcnt lgkmcnt(0)
	v_mfma_f32_16x16x32_bf16 v[12:15], v[180:183], v[230:233], v[12:15]
	v_mfma_f32_16x16x32_bf16 v[8:11], v[184:187], v[230:233], v[8:11]
	v_mfma_f32_16x16x32_bf16 v[4:7], v[188:191], v[230:233], v[4:7]
	v_mfma_f32_16x16x32_bf16 v[0:3], v[192:195], v[230:233], v[0:3]
	s_setprio 0
	v_mov_b32_e32 v80, v210
	s_waitcnt vmcnt(0)
	s_barrier
	s_cmp_eq_u32 s90, 2
	v_ashrrev_i32_e32 v179, 1, v80
	v_and_b32_e32 v179, 0xffffff80, v179
	v_add_u32_e32 v179, s67, v179
	v_and_or_b32 v180, v80, 15, v179
	s_cselect_b64 s[38:39], -1, 0
	v_ashrrev_i32_e32 v181, 31, v180
	v_mov_b32_e32 v182, 1.0
	s_and_b64 vcc, exec, s[38:39]
	s_cbranch_vccz .LBB0_1104
	v_lshl_add_u64 v[182:183], v[180:181], 2, s[42:43]
	global_load_dword v182, v[182:183], off

; template <bool LOWREG = false>
; __device__ __forceinline__ void gemm_core(const bf16_t* __restrict__ A, int lda, const bf16_t* __restrict__ Bt, int ldb, int K, f32x4 (&acc)[8][4], unsigned char* smem, int tid) {
;     ...
;     for (int kt = 0; kt < nk; ++kt) {
;         const int st = kt & 1;
;         const bool more = kt + 1 < nk;
;         const unsigned char* sb = smem + st * G_STAGE;
;         if constexpr (!LOWREG) {
; #pragma unroll
;         for (int ks = 0; ks < 2; ++ks) {
;             bf16x8 bfr[4], af[8];
;             const int co = ((ks * 4 + kq) ^ swz) * 16;
; #pragma unroll
;             for (int ni = 0; ni < 4; ++ni) bfr[ni] = *(const bf16x8*)(sb + boff + ni * 2048 + co);
; #pragma unroll
;             for (int mi = 0; mi < 8; ++mi) af[mi] = *(const bf16x8*)(sb + aoff + mi * 2048 + co);
;             if (more) { G_ISSUE1(kt + 1, st ^ 1, ks * 2); G_ISSUE1(kt + 1, st ^ 1, ks * 2 + 1); }
;             __builtin_amdgcn_sched_barrier(0);
;             __builtin_amdgcn_s_setprio(1);
; #pragma unroll
;             for (int mi = 0; mi < 8; ++mi)
; #pragma unroll
;                 for (int ni = 0; ni < 4; ++ni) acc[mi][ni] = __builtin_amdgcn_mfma_f32_16x16x32_bf16(bfr[ni], af[mi], acc[mi][ni], 0, 0, 0);
;             __builtin_amdgcn_s_setprio(0);
;             __builtin_amdgcn_sched_barrier(0);
;         }
.LBB0_1286:
	s_and_b32 s27, s26, 0x10000
	s_add_i32 s28, s27, 0
	s_xor_b32 s27, s27, 0x10000
	v_add_u32_e32 v80, s28, v147
	v_add_u32_e32 v179, s28, v149
	s_add_i32 s27, s25, s27
	v_add_u32_e32 v162, v80, v148
	v_add_u32_e32 v196, v179, v148
	v_lshl_add_u64 v[200:201], v[130:131], 0, s[44:45]
	s_mov_b32 m0, s27
	ds_read_b128 v[150:153], v162 offset:32768
	ds_read_b128 v[154:157], v162 offset:34816
	ds_read_b128 v[158:161], v162 offset:36864
	ds_read_b128 v[162:165], v162 offset:38912
	ds_read_b128 v[166:169], v196
	ds_read_b128 v[170:173], v196 offset:2048
	ds_read_b128 v[174:177], v196 offset:4096
	ds_read_b128 v[180:183], v196 offset:6144
	ds_read_b128 v[184:187], v196 offset:8192
	ds_read_b128 v[188:191], v196 offset:10240
	ds_read_b128 v[192:195], v196 offset:12288
	ds_read_b128 v[196:199], v196 offset:14336
	global_load_lds_dwordx4 v[200:201], off
	v_lshl_add_u64 v[200:201], v[138:139], 0, s[44:45]
	s_add_i32 m0, s27, 0x8000
	s_nop 0
	global_load_lds_dwordx4 v[200:201], off
	v_lshl_add_u64 v[200:201], v[132:133], 0, s[44:45]
	s_add_i32 m0, s27, 0x2000
	s_nop 0
	global_load_lds_dwordx4 v[200:201], off
	v_lshl_add_u64 v[200:201], v[140:141], 0, s[44:45]
	s_add_i32 m0, s27, 0xa000
	s_nop 0
	global_load_lds_dwordx4 v[200:201], off
	s_setprio 1
	s_waitcnt lgkmcnt(7)
	v_mfma_f32_16x16x32_bf16 v[126:129], v[150:153], v[166:169], v[126:129]
	v_mfma_f32_16x16x32_bf16 v[122:125], v[154:157], v[166:169], v[122:125]
	v_mfma_f32_16x16x32_bf16 v[118:121], v[158:161], v[166:169], v[118:121]
	v_mfma_f32_16x16x32_bf16 v[114:117], v[162:165], v[166:169], v[114:117]
	s_waitcnt lgkmcnt(6)
	v_mfma_f32_16x16x32_bf16 v[110:113], v[150:153], v[170:173], v[110:113]
	v_mfma_f32_16x16x32_bf16 v[106:109], v[154:157], v[170:173], v[106:109]
	v_mfma_f32_16x16x32_bf16 v[102:105], v[158:161], v[170:173], v[102:105]
	v_mfma_f32_16x16x32_bf16 v[98:101], v[162:165], v[170:173], v[98:101]
	s_waitcnt lgkmcnt(5)
	v_mfma_f32_16x16x32_bf16 v[94:97], v[150:153], v[174:177], v[94:97]
	v_mfma_f32_16x16x32_bf16 v[90:93], v[154:157], v[174:177], v[90:93]
	v_mfma_f32_16x16x32_bf16 v[86:89], v[158:161], v[174:177], v[86:89]
	v_mfma_f32_16x16x32_bf16 v[82:85], v[162:165], v[174:177], v[82:85]
	s_waitcnt lgkmcnt(4)
	v_mfma_f32_16x16x32_bf16 v[76:79], v[150:153], v[180:183], v[76:79]
	v_mfma_f32_16x16x32_bf16 v[72:75], v[154:157], v[180:183], v[72:75]
	v_mfma_f32_16x16x32_bf16 v[68:71], v[158:161], v[180:183], v[68:71]
	v_mfma_f32_16x16x32_bf16 v[64:67], v[162:165], v[180:183], v[64:67]
	s_waitcnt lgkmcnt(3)
	v_mfma_f32_16x16x32_bf16 v[60:63], v[150:153], v[184:187], v[60:63]
	v_mfma_f32_16x16x32_bf16 v[56:59], v[154:157], v[184:187], v[56:59]
	v_mfma_f32_16x16x32_bf16 v[52:55], v[158:161], v[184:187], v[52:55]
	v_mfma_f32_16x16x32_bf16 v[48:51], v[162:165], v[184:187], v[48:51]
	s_waitcnt lgkmcnt(2)
	v_mfma_f32_16x16x32_bf16 v[44:47], v[150:153], v[188:191], v[44:47]
	v_mfma_f32_16x16x32_bf16 v[40:43], v[154:157], v[188:191], v[40:43]
	v_mfma_f32_16x16x32_bf16 v[36:39], v[158:161], v[188:191], v[36:39]
	v_mfma_f32_16x16x32_bf16 v[32:35], v[162:165], v[188:191], v[32:35]
	s_waitcnt lgkmcnt(1)
	v_mfma_f32_16x16x32_bf16 v[28:31], v[150:153], v[192:195], v[28:31]
	v_mfma_f32_16x16x32_bf16 v[24:27], v[154:157], v[192:195], v[24:27]
	v_mfma_f32_16x16x32_bf16 v[20:23], v[158:161], v[192:195], v[20:23]
	v_mfma_f32_16x16x32_bf16 v[16:19], v[162:165], v[192:195], v[16:19]
	s_waitcnt lgkmcnt(0)
	v_mfma_f32_16x16x32_bf16 v[12:15], v[150:153], v[196:199], v[12:15]
	v_mfma_f32_16x16x32_bf16 v[8:11], v[154:157], v[196:199], v[8:11]
	v_mfma_f32_16x16x32_bf16 v[4:7], v[158:161], v[196:199], v[4:7]
	v_mfma_f32_16x16x32_bf16 v[0:3], v[162:165], v[196:199], v[0:3]
	s_setprio 0
	v_add_u32_e32 v80, v80, v146
	ds_read_b128 v[150:153], v80 offset:32768
	ds_read_b128 v[154:157], v80 offset:34816
	ds_read_b128 v[158:161], v80 offset:36864
	ds_read_b128 v[162:165], v80 offset:38912
	v_add_u32_e32 v80, v179, v146
	v_lshl_add_u64 v[200:201], v[134:135], 0, s[44:45]
	s_add_i32 m0, s27, 0x4000
	ds_read_b128 v[166:169], v80
	ds_read_b128 v[170:173], v80 offset:2048
	ds_read_b128 v[174:177], v80 offset:4096
	ds_read_b128 v[180:183], v80 offset:6144
	ds_read_b128 v[184:187], v80 offset:8192
	ds_read_b128 v[188:191], v80 offset:10240
	ds_read_b128 v[192:195], v80 offset:12288
	ds_read_b128 v[196:199], v80 offset:14336
	global_load_lds_dwordx4 v[200:201], off
	v_lshl_add_u64 v[200:201], v[142:143], 0, s[44:45]
	s_add_i32 m0, s27, 0xc000
	s_nop 0
	global_load_lds_dwordx4 v[200:201], off
	v_lshl_add_u64 v[200:201], v[136:137], 0, s[44:45]
	s_add_i32 m0, s27, 0x6000
	s_nop 0
	global_load_lds_dwordx4 v[200:201], off
	v_lshl_add_u64 v[200:201], v[144:145], 0, s[44:45]
	s_add_i32 m0, s27, 0xe000
	s_nop 0
	global_load_lds_dwordx4 v[200:201], off
	s_setprio 1
	s_waitcnt lgkmcnt(7)
	v_mfma_f32_16x16x32_bf16 v[126:129], v[150:153], v[166:169], v[126:129]
	v_mfma_f32_16x16x32_bf16 v[122:125], v[154:157], v[166:169], v[122:125]
	v_mfma_f32_16x16x32_bf16 v[118:121], v[158:161], v[166:169], v[118:121]
	v_mfma_f32_16x16x32_bf16 v[114:117], v[162:165], v[166:169], v[114:117]
	s_waitcnt lgkmcnt(6)
	v_mfma_f32_16x16x32_bf16 v[110:113], v[150:153], v[170:173], v[110:113]
	v_mfma_f32_16x16x32_bf16 v[106:109], v[154:157], v[170:173], v[106:109]
	v_mfma_f32_16x16x32_bf16 v[102:105], v[158:161], v[170:173], v[102:105]
	v_mfma_f32_16x16x32_bf16 v[98:101], v[162:165], v[170:173], v[98:101]
	s_waitcnt lgkmcnt(5)
	v_mfma_f32_16x16x32_bf16 v[94:97], v[150:153], v[174:177], v[94:97]
	v_mfma_f32_16x16x32_bf16 v[90:93], v[154:157], v[174:177], v[90:93]
	v_mfma_f32_16x16x32_bf16 v[86:89], v[158:161], v[174:177], v[86:89]
	v_mfma_f32_16x16x32_bf16 v[82:85], v[162:165], v[174:177], v[82:85]
	s_waitcnt lgkmcnt(4)
; template <bool LOWREG = false>
; __device__ __forceinline__ void gemm_core(const bf16_t* __restrict__ A, int lda, const bf16_t* __restrict__ Bt, int ldb, int K, f32x4 (&acc)[8][4], unsigned char* smem, int tid) {
;     ...
;     for (int kt = 0; kt < nk; ++kt) {
;         const int st = kt & 1;
;         const bool more = kt + 1 < nk;
;         const unsigned char* sb = smem + st * G_STAGE;
;         if constexpr (!LOWREG) {
; #pragma unroll
;         for (int ks = 0; ks < 2; ++ks) {
;             bf16x8 bfr[4], af[8];
;             const int co = ((ks * 4 + kq) ^ swz) * 16;
; #pragma unroll
;             for (int ni = 0; ni < 4; ++ni) bfr[ni] = *(const bf16x8*)(sb + boff + ni * 2048 + co);
; #pragma unroll
;             for (int mi = 0; mi < 8; ++mi) af[mi] = *(const bf16x8*)(sb + aoff + mi * 2048 + co);
;             if (more) { G_ISSUE1(kt + 1, st ^ 1, ks * 2); G_ISSUE1(kt + 1, st ^ 1, ks * 2 + 1); }
;             __builtin_amdgcn_sched_barrier(0);
;             __builtin_amdgcn_s_setprio(1);
; #pragma unroll
;             for (int mi = 0; mi < 8; ++mi)
; #pragma unroll
;                 for (int ni = 0; ni < 4; ++ni) acc[mi][ni] = __builtin_amdgcn_mfma_f32_16x16x32_bf16(bfr[ni], af[mi], acc[mi][ni], 0, 0, 0);
;             __builtin_amdgcn_s_setprio(0);
;             __builtin_amdgcn_sched_barrier(0);
;         }
;         } else {
; #pragma unroll
;         for (int ks = 0; ks < 2; ++ks) {
;             bf16x8 bfr[4];
;             const int co = ((ks * 4 + kq) ^ swz) * 16;
; #pragma unroll
;             for (int ni = 0; ni < 4; ++ni) bfr[ni] = *(const bf16x8*)(sb + boff + ni * 2048 + co);
; #pragma unroll
;             for (int mh = 0; mh < 2; ++mh) {
;                 bf16x8 af[4];
; #pragma unroll
;                 for (int mi = 0; mi < 4; ++mi) af[mi] = *(const bf16x8*)(sb + aoff + (mh * 4 + mi) * 2048 + co);
;                 if (more) G_ISSUE1(kt + 1, st ^ 1, ks * 2 + mh);
;                 __builtin_amdgcn_sched_barrier(0);
;                 __builtin_amdgcn_s_setprio(1);
; #pragma unroll
;                 for (int mi = 0; mi < 4; ++mi)
; #pragma unroll
;                     for (int ni = 0; ni < 4; ++ni) acc[mh * 4 + mi][ni] = __builtin_amdgcn_mfma_f32_16x16x32_bf16(bfr[ni], af[mi], acc[mh * 4 + mi][ni], 0, 0, 0);
;                 __builtin_amdgcn_s_setprio(0);
;                 __builtin_amdgcn_sched_barrier(0);
;             }
;         }
	v_mfma_f32_16x16x32_bf16 v[76:79], v[150:153], v[180:183], v[76:79]
	v_mfma_f32_16x16x32_bf16 v[72:75], v[154:157], v[180:183], v[72:75]
	v_mfma_f32_16x16x32_bf16 v[68:71], v[158:161], v[180:183], v[68:71]
	v_mfma_f32_16x16x32_bf16 v[64:67], v[162:165], v[180:183], v[64:67]
	s_waitcnt lgkmcnt(3)
	v_mfma_f32_16x16x32_bf16 v[60:63], v[150:153], v[184:187], v[60:63]
	v_mfma_f32_16x16x32_bf16 v[56:59], v[154:157], v[184:187], v[56:59]
	v_mfma_f32_16x16x32_bf16 v[52:55], v[158:161], v[184:187], v[52:55]
	v_mfma_f32_16x16x32_bf16 v[48:51], v[162:165], v[184:187], v[48:51]
	s_waitcnt lgkmcnt(2)
	v_mfma_f32_16x16x32_bf16 v[44:47], v[150:153], v[188:191], v[44:47]
	v_mfma_f32_16x16x32_bf16 v[40:43], v[154:157], v[188:191], v[40:43]
	v_mfma_f32_16x16x32_bf16 v[36:39], v[158:161], v[188:191], v[36:39]
	v_mfma_f32_16x16x32_bf16 v[32:35], v[162:165], v[188:191], v[32:35]
	s_waitcnt lgkmcnt(1)
	v_mfma_f32_16x16x32_bf16 v[28:31], v[150:153], v[192:195], v[28:31]
	v_mfma_f32_16x16x32_bf16 v[24:27], v[154:157], v[192:195], v[24:27]
	v_mfma_f32_16x16x32_bf16 v[20:23], v[158:161], v[192:195], v[20:23]
	v_mfma_f32_16x16x32_bf16 v[16:19], v[162:165], v[192:195], v[16:19]
	s_waitcnt lgkmcnt(0)
	v_mfma_f32_16x16x32_bf16 v[12:15], v[150:153], v[196:199], v[12:15]
	v_mfma_f32_16x16x32_bf16 v[8:11], v[154:157], v[196:199], v[8:11]
	v_mfma_f32_16x16x32_bf16 v[4:7], v[158:161], v[196:199], v[4:7]
	v_mfma_f32_16x16x32_bf16 v[0:3], v[162:165], v[196:199], v[0:3]
	s_setprio 0
	s_add_i32 s26, s26, 0x10000
	s_waitcnt vmcnt(0)
	s_add_u32 s44, s44, 0x80
	s_addc_u32 s45, s45, 0
	s_cmpk_lg_i32 s44, 0x780
	s_waitcnt vmcnt(0)
	s_barrier
	s_cbranch_scc1 .LBB0_1286
	s_add_i32 s25, 0, 0x10000
	v_add_u32_e32 v80, s25, v149
	v_add_u32_e32 v149, v80, v148
	ds_read_b128 v[130:133], v149 offset:14336
	ds_read_b128 v[134:137], v149 offset:12288
	ds_read_b128 v[138:141], v149 offset:10240
	ds_read_b128 v[142:145], v149 offset:8192
	ds_read_b128 v[150:153], v149 offset:6144
	ds_read_b128 v[154:157], v149 offset:4096
	ds_read_b128 v[158:161], v149 offset:2048
	ds_read_b128 v[162:165], v149
	v_add_u32_e32 v147, s25, v147
	v_add_u32_e32 v148, v147, v148
	ds_read_b128 v[166:169], v148 offset:38912
	ds_read_b128 v[170:173], v148 offset:36864
	ds_read_b128 v[174:177], v148 offset:34816
	ds_read_b128 v[180:183], v148 offset:32768
	s_setprio 1
	s_waitcnt lgkmcnt(3)
	v_mfma_f32_16x16x32_bf16 v[114:117], v[166:169], v[162:165], v[114:117]
	v_mfma_f32_16x16x32_bf16 v[98:101], v[166:169], v[158:161], v[98:101]
	v_mfma_f32_16x16x32_bf16 v[82:85], v[166:169], v[154:157], v[82:85]
	v_mfma_f32_16x16x32_bf16 v[64:67], v[166:169], v[150:153], v[64:67]
	v_mfma_f32_16x16x32_bf16 v[48:51], v[166:169], v[142:145], v[48:51]
	v_mfma_f32_16x16x32_bf16 v[32:35], v[166:169], v[138:141], v[32:35]
	v_mfma_f32_16x16x32_bf16 v[16:19], v[166:169], v[134:137], v[16:19]
	v_mfma_f32_16x16x32_bf16 v[0:3], v[166:169], v[130:133], v[0:3]
	s_waitcnt lgkmcnt(2)
	v_mfma_f32_16x16x32_bf16 v[118:121], v[170:173], v[162:165], v[118:121]
	v_mfma_f32_16x16x32_bf16 v[102:105], v[170:173], v[158:161], v[102:105]
	v_mfma_f32_16x16x32_bf16 v[86:89], v[170:173], v[154:157], v[86:89]
	v_mfma_f32_16x16x32_bf16 v[68:71], v[170:173], v[150:153], v[68:71]
	v_mfma_f32_16x16x32_bf16 v[52:55], v[170:173], v[142:145], v[52:55]
	v_mfma_f32_16x16x32_bf16 v[36:39], v[170:173], v[138:141], v[36:39]
	v_mfma_f32_16x16x32_bf16 v[20:23], v[170:173], v[134:137], v[20:23]
	v_mfma_f32_16x16x32_bf16 v[4:7], v[170:173], v[130:133], v[4:7]
	s_waitcnt lgkmcnt(1)
	v_mfma_f32_16x16x32_bf16 v[122:125], v[174:177], v[162:165], v[122:125]
	v_mfma_f32_16x16x32_bf16 v[106:109], v[174:177], v[158:161], v[106:109]
	v_mfma_f32_16x16x32_bf16 v[90:93], v[174:177], v[154:157], v[90:93]
	v_mfma_f32_16x16x32_bf16 v[72:75], v[174:177], v[150:153], v[72:75]
	v_mfma_f32_16x16x32_bf16 v[56:59], v[174:177], v[142:145], v[56:59]
	v_mfma_f32_16x16x32_bf16 v[40:43], v[174:177], v[138:141], v[40:43]
	v_mfma_f32_16x16x32_bf16 v[24:27], v[174:177], v[134:137], v[24:27]
	v_mfma_f32_16x16x32_bf16 v[8:11], v[174:177], v[130:133], v[8:11]
	s_waitcnt lgkmcnt(0)
	v_mfma_f32_16x16x32_bf16 v[126:129], v[180:183], v[162:165], v[126:129]
	v_mfma_f32_16x16x32_bf16 v[110:113], v[180:183], v[158:161], v[110:113]
	v_mfma_f32_16x16x32_bf16 v[94:97], v[180:183], v[154:157], v[94:97]
	v_mfma_f32_16x16x32_bf16 v[76:79], v[180:183], v[150:153], v[76:79]
	v_mfma_f32_16x16x32_bf16 v[60:63], v[180:183], v[142:145], v[60:63]
	v_mfma_f32_16x16x32_bf16 v[44:47], v[180:183], v[138:141], v[44:47]
	v_mfma_f32_16x16x32_bf16 v[28:31], v[180:183], v[134:137], v[28:31]
	v_mfma_f32_16x16x32_bf16 v[12:15], v[180:183], v[130:133], v[12:15]
	s_setprio 0
	v_add_u32_e32 v80, v80, v146
	ds_read_b128 v[130:133], v80 offset:14336
	ds_read_b128 v[134:137], v80 offset:12288
	ds_read_b128 v[138:141], v80 offset:10240
	ds_read_b128 v[142:145], v80 offset:8192
	ds_read_b128 v[148:151], v80 offset:6144
	ds_read_b128 v[152:155], v80 offset:4096
	ds_read_b128 v[156:159], v80 offset:2048
	ds_read_b128 v[160:163], v80
	v_add_u32_e32 v80, v147, v146
	ds_read_b128 v[164:167], v80 offset:38912
	ds_read_b128 v[168:171], v80 offset:36864
	ds_read_b128 v[172:175], v80 offset:34816
	ds_read_b128 v[180:183], v80 offset:32768
	s_setprio 1
	s_waitcnt lgkmcnt(3)
	v_mfma_f32_16x16x32_bf16 v[114:117], v[164:167], v[160:163], v[114:117]
	v_mfma_f32_16x16x32_bf16 v[98:101], v[164:167], v[156:159], v[98:101]
	v_mfma_f32_16x16x32_bf16 v[82:85], v[164:167], v[152:155], v[82:85]
	v_mfma_f32_16x16x32_bf16 v[64:67], v[164:167], v[148:151], v[64:67]
	v_mfma_f32_16x16x32_bf16 v[48:51], v[164:167], v[142:145], v[48:51]
	v_mfma_f32_16x16x32_bf16 v[32:35], v[164:167], v[138:141], v[32:35]
	v_mfma_f32_16x16x32_bf16 v[16:19], v[164:167], v[134:137], v[16:19]
	v_mfma_f32_16x16x32_bf16 v[0:3], v[164:167], v[130:133], v[0:3]
	s_waitcnt lgkmcnt(2)
; template <bool LOWREG = false>
; __device__ __forceinline__ void gemm_core(const bf16_t* __restrict__ A, int lda, const bf16_t* __restrict__ Bt, int ldb, int K, f32x4 (&acc)[8][4], unsigned char* smem, int tid) {
;     ...
;         for (int ks = 0; ks < 2; ++ks) {
;             bf16x8 bfr[4], af[8];
;             const int co = ((ks * 4 + kq) ^ swz) * 16;
; #pragma unroll
;             for (int ni = 0; ni < 4; ++ni) bfr[ni] = *(const bf16x8*)(sb + boff + ni * 2048 + co);
; #pragma unroll
;             for (int mi = 0; mi < 8; ++mi) af[mi] = *(const bf16x8*)(sb + aoff + mi * 2048 + co);
;             if (more) { G_ISSUE1(kt + 1, st ^ 1, ks * 2); G_ISSUE1(kt + 1, st ^ 1, ks * 2 + 1); }
;             __builtin_amdgcn_sched_barrier(0);
;             __builtin_amdgcn_s_setprio(1);
; #pragma unroll
;             for (int mi = 0; mi < 8; ++mi)
; #pragma unroll
;                 for (int ni = 0; ni < 4; ++ni) acc[mi][ni] = __builtin_amdgcn_mfma_f32_16x16x32_bf16(bfr[ni], af[mi], acc[mi][ni], 0, 0, 0);
;             __builtin_amdgcn_s_setprio(0);
;             __builtin_amdgcn_sched_barrier(0);
;         }
; __device__ void out_phase(const Params& p, int l, int hb, const float* xsrc, unsigned char* smem) {
;     ...
;         for (int mi = 0; mi < 8; ++mi) {
;             const int row = m0 + wm * 128 + mi * 16 + idx; const size_t rg = (size_t)hb * TP + row; const int b = (int)(rg / SEQ);
;             const float* gate = (const float*)(p.ws + WS_MOD) + (size_t)(l * 4 + b) * 3072 + 2048;
; #pragma unroll
;             for (int ni = 0; ni < 4; ++ni) {
;                 const int col = n0 + wn * 64 + ni * 16 + 4 * kq;
;                 const f32x4 xv = *(const f32x4*)(xsrc + rg * 1024 + col), gv = *(const f32x4*)(gate + col);
;                 *(f32x4*)(p.out + rg * 1024 + col) = xv + gv * acc[mi][ni];
;             }
	v_mfma_f32_16x16x32_bf16 v[192:195], v[168:171], v[160:163], v[118:121]
	v_mfma_f32_16x16x32_bf16 v[102:105], v[168:171], v[156:159], v[102:105]
	v_mfma_f32_16x16x32_bf16 v[86:89], v[168:171], v[152:155], v[86:89]
	v_mfma_f32_16x16x32_bf16 v[68:71], v[168:171], v[148:151], v[68:71]
	v_mfma_f32_16x16x32_bf16 v[52:55], v[168:171], v[142:145], v[52:55]
	v_mfma_f32_16x16x32_bf16 v[36:39], v[168:171], v[138:141], v[36:39]
	v_mfma_f32_16x16x32_bf16 v[20:23], v[168:171], v[134:137], v[20:23]
	v_mfma_f32_16x16x32_bf16 v[4:7], v[168:171], v[130:133], v[4:7]
	s_waitcnt lgkmcnt(1)
	v_mfma_f32_16x16x32_bf16 v[188:191], v[172:175], v[160:163], v[122:125]
	v_mfma_f32_16x16x32_bf16 v[106:109], v[172:175], v[156:159], v[106:109]
	v_mfma_f32_16x16x32_bf16 v[90:93], v[172:175], v[152:155], v[90:93]
	v_mfma_f32_16x16x32_bf16 v[72:75], v[172:175], v[148:151], v[72:75]
	v_mfma_f32_16x16x32_bf16 v[56:59], v[172:175], v[142:145], v[56:59]
	v_mfma_f32_16x16x32_bf16 v[40:43], v[172:175], v[138:141], v[40:43]
	v_mfma_f32_16x16x32_bf16 v[24:27], v[172:175], v[134:137], v[24:27]
	v_mfma_f32_16x16x32_bf16 v[8:11], v[172:175], v[130:133], v[8:11]
	s_waitcnt lgkmcnt(0)
	v_mfma_f32_16x16x32_bf16 v[184:187], v[180:183], v[160:163], v[126:129]
	v_mfma_f32_16x16x32_bf16 v[110:113], v[180:183], v[156:159], v[110:113]
	v_mfma_f32_16x16x32_bf16 v[94:97], v[180:183], v[152:155], v[94:97]
	v_mfma_f32_16x16x32_bf16 v[76:79], v[180:183], v[148:151], v[76:79]
	v_mfma_f32_16x16x32_bf16 v[60:63], v[180:183], v[142:145], v[60:63]
	v_mfma_f32_16x16x32_bf16 v[44:47], v[180:183], v[138:141], v[44:47]
	v_mfma_f32_16x16x32_bf16 v[28:31], v[180:183], v[134:137], v[28:31]
	v_mfma_f32_16x16x32_bf16 v[12:15], v[180:183], v[130:133], v[12:15]
	s_setprio 0
	v_mov_b32_e32 v80, v210
	s_waitcnt vmcnt(0)
	s_barrier
	v_mov_b64_e32 v[126:127], s[40:41]
	v_ashrrev_i32_e32 v119, 1, v80
	v_and_b32_e32 v119, 0xffffff80, v119
	v_add_u32_e32 v119, s42, v119
	v_and_b32_e32 v118, 0xc0, v80
	v_and_or_b32 v124, v80, 15, v119
	v_lshrrev_b32_e32 v80, 2, v80
	v_and_b32_e32 v80, 12, v80
	v_ashrrev_i32_e32 v125, 31, v124
	v_or3_b32 v80, v118, v80, s24
	v_lshl_add_u64 v[118:119], s[86:87], 0, v[124:125]
	v_alignbit_b32 v120, v119, v118, 13
	v_add_u32_e32 v120, s10, v120
	v_mad_i64_i32 v[120:121], s[24:25], v120, s33, v[126:127]
	v_lshlrev_b64 v[118:119], 12, v[118:119]
	v_lshl_add_u64 v[136:137], v[120:121], 0, s[84:85]
	v_lshl_add_u64 v[120:121], s[36:37], 0, v[118:119]
	v_lshlrev_b32_e32 v80, 2, v80
	v_lshl_add_u64 v[138:139], v[120:121], 0, v[80:81]
	v_lshl_add_u64 v[128:129], v[136:137], 0, v[80:81]
	v_lshl_add_u64 v[122:123], s[38:39], 0, v[118:119]
	global_load_dwordx4 v[118:121], v[138:139], off
	v_lshl_add_u64 v[140:141], v[122:123], 0, v[80:81]
	global_load_dwordx4 v[128:131], v[128:129], off
	s_add_i32 s23, s23, s8
	s_add_i32 s22, s22, s8
	s_add_i32 s21, s21, s6
	s_cmpk_lt_i32 s23, 0x100
	s_waitcnt vmcnt(0)
	v_pk_fma_f32 v[120:121], v[186:187], v[130:131], v[120:121]
	v_pk_fma_f32 v[118:119], v[184:185], v[128:129], v[118:119]
	global_store_dwordx4 v[140:141], v[118:121], off
	global_load_dwordx4 v[120:123], v[138:139], off offset:64
	s_nop 0
	v_or_b32_e32 v118, 64, v80
	v_mov_b32_e32 v119, v81
	v_lshl_add_u64 v[128:129], v[136:137], 0, v[118:119]
	global_load_dwordx4 v[128:131], v[128:129], off
	s_waitcnt vmcnt(0)
	v_pk_fma_f32 v[122:123], v[190:191], v[130:131], v[122:123]
	v_pk_fma_f32 v[120:121], v[188:189], v[128:129], v[120:121]
	global_store_dwordx4 v[140:141], v[120:123], off offset:64
	global_load_dwordx4 v[128:131], v[138:139], off offset:128
	s_nop 0
	v_or_b32_e32 v120, 0x80, v80
	v_mov_b32_e32 v121, v81
	v_lshl_add_u64 v[122:123], v[136:137], 0, v[120:121]
	global_load_dwordx4 v[132:135], v[122:123], off
	v_or_b32_e32 v122, 0xc0, v80
	v_mov_b32_e32 v123, v81
	s_waitcnt vmcnt(0)
	v_pk_fma_f32 v[130:131], v[194:195], v[134:135], v[130:131]
	v_pk_fma_f32 v[128:129], v[192:193], v[132:133], v[128:129]
	global_store_dwordx4 v[140:141], v[128:131], off offset:128
	v_lshl_add_u64 v[132:133], v[136:137], 0, v[122:123]
	global_load_dwordx4 v[128:131], v[138:139], off offset:192
	s_nop 0
	global_load_dwordx4 v[132:135], v[132:133], off
	s_waitcnt vmcnt(0)
	v_pk_fma_f32 v[116:117], v[116:117], v[134:135], v[130:131]
	v_pk_fma_f32 v[114:115], v[114:115], v[132:133], v[128:129]
	global_store_dwordx4 v[140:141], v[114:117], off offset:192
	s_nop 1
	v_or_b32_e32 v114, 16, v124
	v_ashrrev_i32_e32 v115, 31, v114
	v_lshl_add_u64 v[114:115], s[86:87], 0, v[114:115]
	v_alignbit_b32 v116, v115, v114, 13
	v_add_u32_e32 v116, s10, v116
	v_mad_i64_i32 v[116:117], s[24:25], v116, s33, v[126:127]
	v_lshlrev_b64 v[114:115], 12, v[114:115]
	v_lshl_add_u64 v[132:133], v[116:117], 0, s[84:85]
	v_lshl_add_u64 v[116:117], s[36:37], 0, v[114:115]
	v_lshl_add_u64 v[136:137], v[116:117], 0, v[80:81]
	v_lshl_add_u64 v[128:129], v[132:133], 0, v[80:81]
	v_lshl_add_u64 v[134:135], s[38:39], 0, v[114:115]
	global_load_dwordx4 v[114:117], v[136:137], off
	s_nop 0
	global_load_dwordx4 v[128:131], v[128:129], off
	s_waitcnt vmcnt(0)
	v_pk_fma_f32 v[112:113], v[112:113], v[130:131], v[116:117]
	v_pk_fma_f32 v[110:111], v[110:111], v[128:129], v[114:115]
	v_lshl_add_u64 v[128:129], v[134:135], 0, v[80:81]
	global_store_dwordx4 v[128:129], v[110:113], off
	v_lshl_add_u64 v[114:115], v[132:133], 0, v[118:119]
	global_load_dwordx4 v[110:113], v[136:137], off offset:64
	s_nop 0
	global_load_dwordx4 v[114:117], v[114:115], off
	s_waitcnt vmcnt(0)
	v_pk_fma_f32 v[108:109], v[108:109], v[116:117], v[112:113]
	v_pk_fma_f32 v[106:107], v[106:107], v[114:115], v[110:111]
	global_store_dwordx4 v[128:129], v[106:109], off offset:64
	v_lshl_add_u64 v[110:111], v[132:133], 0, v[120:121]
	global_load_dwordx4 v[106:109], v[136:137], off offset:128
	s_nop 0
	global_load_dwordx4 v[110:113], v[110:111], off
	s_waitcnt vmcnt(0)
; __device__ void out_phase(const Params& p, int l, int hb, const float* xsrc, unsigned char* smem) {
;     ...
;         for (int mi = 0; mi < 8; ++mi) {
;             const int row = m0 + wm * 128 + mi * 16 + idx; const size_t rg = (size_t)hb * TP + row; const int b = (int)(rg / SEQ);
;             const float* gate = (const float*)(p.ws + WS_MOD) + (size_t)(l * 4 + b) * 3072 + 2048;
; #pragma unroll
;             for (int ni = 0; ni < 4; ++ni) {
;                 const int col = n0 + wn * 64 + ni * 16 + 4 * kq;
;                 const f32x4 xv = *(const f32x4*)(xsrc + rg * 1024 + col), gv = *(const f32x4*)(gate + col);
;                 *(f32x4*)(p.out + rg * 1024 + col) = xv + gv * acc[mi][ni];
;             }
	v_pk_fma_f32 v[104:105], v[104:105], v[112:113], v[108:109]
	v_pk_fma_f32 v[102:103], v[102:103], v[110:111], v[106:107]
	global_store_dwordx4 v[128:129], v[102:105], off offset:128
	v_lshl_add_u64 v[106:107], v[132:133], 0, v[122:123]
	global_load_dwordx4 v[102:105], v[136:137], off offset:192
	s_nop 0
	global_load_dwordx4 v[106:109], v[106:107], off
	s_waitcnt vmcnt(0)
	v_pk_fma_f32 v[100:101], v[100:101], v[108:109], v[104:105]
	v_pk_fma_f32 v[98:99], v[98:99], v[106:107], v[102:103]
	global_store_dwordx4 v[128:129], v[98:101], off offset:192
	s_nop 1
	v_or_b32_e32 v98, 32, v124
	v_ashrrev_i32_e32 v99, 31, v98
	v_lshl_add_u64 v[98:99], s[86:87], 0, v[98:99]
	v_alignbit_b32 v100, v99, v98, 13
	v_add_u32_e32 v100, s10, v100
	v_mad_i64_i32 v[100:101], s[24:25], v100, s33, v[126:127]
	v_lshlrev_b64 v[98:99], 12, v[98:99]
	v_lshl_add_u64 v[106:107], v[100:101], 0, s[84:85]
	v_lshl_add_u64 v[100:101], s[36:37], 0, v[98:99]
	v_lshl_add_u64 v[110:111], v[100:101], 0, v[80:81]
	v_lshl_add_u64 v[102:103], v[106:107], 0, v[80:81]
	v_lshl_add_u64 v[108:109], s[38:39], 0, v[98:99]
	global_load_dwordx4 v[98:101], v[110:111], off
	s_nop 0
	global_load_dwordx4 v[102:105], v[102:103], off
	s_waitcnt vmcnt(0)
	v_pk_fma_f32 v[96:97], v[96:97], v[104:105], v[100:101]
	v_pk_fma_f32 v[94:95], v[94:95], v[102:103], v[98:99]
	v_lshl_add_u64 v[102:103], v[108:109], 0, v[80:81]
	global_store_dwordx4 v[102:103], v[94:97], off
	v_lshl_add_u64 v[98:99], v[106:107], 0, v[118:119]
	global_load_dwordx4 v[94:97], v[110:111], off offset:64
	s_nop 0
	global_load_dwordx4 v[98:101], v[98:99], off
	s_waitcnt vmcnt(0)
	v_pk_fma_f32 v[92:93], v[92:93], v[100:101], v[96:97]
	v_pk_fma_f32 v[90:91], v[90:91], v[98:99], v[94:95]
	global_store_dwordx4 v[102:103], v[90:93], off offset:64
	v_lshl_add_u64 v[94:95], v[106:107], 0, v[120:121]
	global_load_dwordx4 v[90:93], v[110:111], off offset:128
	s_nop 0
	global_load_dwordx4 v[94:97], v[94:95], off
	s_waitcnt vmcnt(0)
	v_pk_fma_f32 v[88:89], v[88:89], v[96:97], v[92:93]
	v_pk_fma_f32 v[86:87], v[86:87], v[94:95], v[90:91]
	global_store_dwordx4 v[102:103], v[86:89], off offset:128
	v_lshl_add_u64 v[90:91], v[106:107], 0, v[122:123]
	global_load_dwordx4 v[86:89], v[110:111], off offset:192
	s_nop 0
	global_load_dwordx4 v[90:93], v[90:91], off
	s_waitcnt vmcnt(0)
	v_pk_fma_f32 v[84:85], v[84:85], v[92:93], v[88:89]
	v_pk_fma_f32 v[82:83], v[82:83], v[90:91], v[86:87]
	global_store_dwordx4 v[102:103], v[82:85], off offset:192
	s_nop 1
	v_or_b32_e32 v82, 48, v124
	v_ashrrev_i32_e32 v83, 31, v82
	v_lshl_add_u64 v[82:83], s[86:87], 0, v[82:83]
	v_alignbit_b32 v84, v83, v82, 13
	v_add_u32_e32 v84, s10, v84
	v_mad_i64_i32 v[84:85], s[24:25], v84, s33, v[126:127]
	v_lshlrev_b64 v[82:83], 12, v[82:83]
	v_lshl_add_u64 v[90:91], v[84:85], 0, s[84:85]
	v_lshl_add_u64 v[84:85], s[36:37], 0, v[82:83]
	v_lshl_add_u64 v[94:95], v[84:85], 0, v[80:81]
	v_lshl_add_u64 v[86:87], v[90:91], 0, v[80:81]
	v_lshl_add_u64 v[92:93], s[38:39], 0, v[82:83]
	global_load_dwordx4 v[82:85], v[94:95], off
	s_nop 0
	global_load_dwordx4 v[86:89], v[86:87], off
	s_waitcnt vmcnt(0)
	v_pk_fma_f32 v[78:79], v[78:79], v[88:89], v[84:85]
	v_pk_fma_f32 v[76:77], v[76:77], v[86:87], v[82:83]
	v_lshl_add_u64 v[86:87], v[92:93], 0, v[80:81]
	global_store_dwordx4 v[86:87], v[76:79], off
	v_lshl_add_u64 v[82:83], v[90:91], 0, v[118:119]
	global_load_dwordx4 v[76:79], v[94:95], off offset:64
	s_nop 0
	global_load_dwordx4 v[82:85], v[82:83], off
	s_waitcnt vmcnt(0)
	v_pk_fma_f32 v[74:75], v[74:75], v[84:85], v[78:79]
	v_pk_fma_f32 v[72:73], v[72:73], v[82:83], v[76:77]
	global_store_dwordx4 v[86:87], v[72:75], off offset:64
	v_lshl_add_u64 v[76:77], v[90:91], 0, v[120:121]
	global_load_dwordx4 v[72:75], v[94:95], off offset:128
	s_nop 0
	global_load_dwordx4 v[76:79], v[76:77], off
	s_waitcnt vmcnt(0)
	v_pk_fma_f32 v[70:71], v[70:71], v[78:79], v[74:75]
	v_pk_fma_f32 v[68:69], v[68:69], v[76:77], v[72:73]
	global_store_dwordx4 v[86:87], v[68:71], off offset:128
	v_lshl_add_u64 v[72:73], v[90:91], 0, v[122:123]
	global_load_dwordx4 v[68:71], v[94:95], off offset:192
	s_nop 0
	global_load_dwordx4 v[72:75], v[72:73], off
	s_waitcnt vmcnt(0)
	v_pk_fma_f32 v[66:67], v[66:67], v[74:75], v[70:71]
	v_pk_fma_f32 v[64:65], v[64:65], v[72:73], v[68:69]
	global_store_dwordx4 v[86:87], v[64:67], off offset:192
	s_nop 1
	v_or_b32_e32 v64, 64, v124
	v_ashrrev_i32_e32 v65, 31, v64
	v_lshl_add_u64 v[64:65], s[86:87], 0, v[64:65]
	v_alignbit_b32 v66, v65, v64, 13
	v_add_u32_e32 v66, s10, v66
	v_mad_i64_i32 v[66:67], s[24:25], v66, s33, v[126:127]
	v_lshlrev_b64 v[64:65], 12, v[64:65]
	v_lshl_add_u64 v[72:73], v[66:67], 0, s[84:85]
	v_lshl_add_u64 v[66:67], s[36:37], 0, v[64:65]
	v_lshl_add_u64 v[76:77], v[66:67], 0, v[80:81]
	v_lshl_add_u64 v[68:69], v[72:73], 0, v[80:81]
	v_lshl_add_u64 v[74:75], s[38:39], 0, v[64:65]
	global_load_dwordx4 v[64:67], v[76:77], off
	s_nop 0
	global_load_dwordx4 v[68:71], v[68:69], off
	s_waitcnt vmcnt(0)
	v_pk_fma_f32 v[62:63], v[62:63], v[70:71], v[66:67]
	v_pk_fma_f32 v[60:61], v[60:61], v[68:69], v[64:65]
	v_lshl_add_u64 v[68:69], v[74:75], 0, v[80:81]
	global_store_dwordx4 v[68:69], v[60:63], off
	v_lshl_add_u64 v[64:65], v[72:73], 0, v[118:119]
	global_load_dwordx4 v[60:63], v[76:77], off offset:64
	s_nop 0
	global_load_dwordx4 v[64:67], v[64:65], off
	s_waitcnt vmcnt(0)
	v_pk_fma_f32 v[58:59], v[58:59], v[66:67], v[62:63]
	v_pk_fma_f32 v[56:57], v[56:57], v[64:65], v[60:61]
	global_store_dwordx4 v[68:69], v[56:59], off offset:64
	v_lshl_add_u64 v[60:61], v[72:73], 0, v[120:121]
	global_load_dwordx4 v[56:59], v[76:77], off offset:128
	s_nop 0
	global_load_dwordx4 v[60:63], v[60:61], off
	s_waitcnt vmcnt(0)
; __device__ void out_phase(const Params& p, int l, int hb, const float* xsrc, unsigned char* smem) {
;     ...
;     for (int t = blockIdx.x; t < 64 * 4; t += gridDim.x) {
;         const int xq = t >> 3, mt = (xq >> 2) * 8 + (t & 7), nt = xq & 3, m0 = mt * 256, n0 = nt * 256;
;         f32x4 acc[8][4];
;         int tid = threadIdx.x;
;         gemm_core(MR + (size_t)m0 * 1024, 1024, Wt + (size_t)n0 * 1024, 1024, 1024, acc, smem, tid);
;         asm volatile("" : "+v"(tid));
;         const int lane = tid & 63, w = tid >> 6, wm = w >> 2, wn = w & 3, idx = lane & 15, kq = lane >> 4;
; #pragma unroll
;         for (int mi = 0; mi < 8; ++mi) {
;             const int row = m0 + wm * 128 + mi * 16 + idx; const size_t rg = (size_t)hb * TP + row; const int b = (int)(rg / SEQ);
;             const float* gate = (const float*)(p.ws + WS_MOD) + (size_t)(l * 4 + b) * 3072 + 2048;
; #pragma unroll
;             for (int ni = 0; ni < 4; ++ni) {
;                 const int col = n0 + wn * 64 + ni * 16 + 4 * kq;
;                 const f32x4 xv = *(const f32x4*)(xsrc + rg * 1024 + col), gv = *(const f32x4*)(gate + col);
;                 *(f32x4*)(p.out + rg * 1024 + col) = xv + gv * acc[mi][ni];
;             }
;         }
;     }
	v_pk_fma_f32 v[54:55], v[54:55], v[62:63], v[58:59]
	v_pk_fma_f32 v[52:53], v[52:53], v[60:61], v[56:57]
	global_store_dwordx4 v[68:69], v[52:55], off offset:128
	v_lshl_add_u64 v[56:57], v[72:73], 0, v[122:123]
	global_load_dwordx4 v[52:55], v[76:77], off offset:192
	s_nop 0
	global_load_dwordx4 v[56:59], v[56:57], off
	s_waitcnt vmcnt(0)
	v_pk_fma_f32 v[50:51], v[50:51], v[58:59], v[54:55]
	v_pk_fma_f32 v[48:49], v[48:49], v[56:57], v[52:53]
	global_store_dwordx4 v[68:69], v[48:51], off offset:192
	s_nop 1
	v_or_b32_e32 v48, 0x50, v124
	v_ashrrev_i32_e32 v49, 31, v48
	v_lshl_add_u64 v[48:49], s[86:87], 0, v[48:49]
	v_alignbit_b32 v50, v49, v48, 13
	v_add_u32_e32 v50, s10, v50
	v_mad_i64_i32 v[50:51], s[24:25], v50, s33, v[126:127]
	v_lshlrev_b64 v[48:49], 12, v[48:49]
	v_lshl_add_u64 v[56:57], v[50:51], 0, s[84:85]
	v_lshl_add_u64 v[50:51], s[36:37], 0, v[48:49]
	v_lshl_add_u64 v[60:61], v[50:51], 0, v[80:81]
	v_lshl_add_u64 v[52:53], v[56:57], 0, v[80:81]
	v_lshl_add_u64 v[58:59], s[38:39], 0, v[48:49]
	global_load_dwordx4 v[48:51], v[60:61], off
	s_nop 0
	global_load_dwordx4 v[52:55], v[52:53], off
	s_waitcnt vmcnt(0)
	v_pk_fma_f32 v[46:47], v[46:47], v[54:55], v[50:51]
	v_pk_fma_f32 v[44:45], v[44:45], v[52:53], v[48:49]
	v_lshl_add_u64 v[52:53], v[58:59], 0, v[80:81]
	global_store_dwordx4 v[52:53], v[44:47], off
	v_lshl_add_u64 v[48:49], v[56:57], 0, v[118:119]
	global_load_dwordx4 v[44:47], v[60:61], off offset:64
	s_nop 0
	global_load_dwordx4 v[48:51], v[48:49], off
	s_waitcnt vmcnt(0)
	v_pk_fma_f32 v[42:43], v[42:43], v[50:51], v[46:47]
	v_pk_fma_f32 v[40:41], v[40:41], v[48:49], v[44:45]
	global_store_dwordx4 v[52:53], v[40:43], off offset:64
	v_lshl_add_u64 v[44:45], v[56:57], 0, v[120:121]
	global_load_dwordx4 v[40:43], v[60:61], off offset:128
	s_nop 0
	global_load_dwordx4 v[44:47], v[44:45], off
	s_waitcnt vmcnt(0)
	v_pk_fma_f32 v[38:39], v[38:39], v[46:47], v[42:43]
	v_pk_fma_f32 v[36:37], v[36:37], v[44:45], v[40:41]
	global_store_dwordx4 v[52:53], v[36:39], off offset:128
	v_lshl_add_u64 v[40:41], v[56:57], 0, v[122:123]
	global_load_dwordx4 v[36:39], v[60:61], off offset:192
	s_nop 0
	global_load_dwordx4 v[40:43], v[40:41], off
	s_waitcnt vmcnt(0)
	v_pk_fma_f32 v[34:35], v[34:35], v[42:43], v[38:39]
	v_pk_fma_f32 v[32:33], v[32:33], v[40:41], v[36:37]
	global_store_dwordx4 v[52:53], v[32:35], off offset:192
	s_nop 1
	v_or_b32_e32 v32, 0x60, v124
	v_ashrrev_i32_e32 v33, 31, v32
	v_lshl_add_u64 v[32:33], s[86:87], 0, v[32:33]
	v_alignbit_b32 v34, v33, v32, 13
	v_add_u32_e32 v34, s10, v34
	v_mad_i64_i32 v[34:35], s[24:25], v34, s33, v[126:127]
	v_lshlrev_b64 v[32:33], 12, v[32:33]
	v_lshl_add_u64 v[40:41], v[34:35], 0, s[84:85]
	v_lshl_add_u64 v[34:35], s[36:37], 0, v[32:33]
	v_lshl_add_u64 v[44:45], v[34:35], 0, v[80:81]
	v_lshl_add_u64 v[36:37], v[40:41], 0, v[80:81]
	v_lshl_add_u64 v[42:43], s[38:39], 0, v[32:33]
	global_load_dwordx4 v[32:35], v[44:45], off
	s_nop 0
	global_load_dwordx4 v[36:39], v[36:37], off
	s_waitcnt vmcnt(0)
	v_pk_fma_f32 v[30:31], v[30:31], v[38:39], v[34:35]
	v_pk_fma_f32 v[28:29], v[28:29], v[36:37], v[32:33]
	v_lshl_add_u64 v[36:37], v[42:43], 0, v[80:81]
	global_store_dwordx4 v[36:37], v[28:31], off
	v_lshl_add_u64 v[32:33], v[40:41], 0, v[118:119]
	global_load_dwordx4 v[28:31], v[44:45], off offset:64
	s_nop 0
	global_load_dwordx4 v[32:35], v[32:33], off
	s_waitcnt vmcnt(0)
	v_pk_fma_f32 v[26:27], v[26:27], v[34:35], v[30:31]
	v_pk_fma_f32 v[24:25], v[24:25], v[32:33], v[28:29]
	global_store_dwordx4 v[36:37], v[24:27], off offset:64
	v_lshl_add_u64 v[28:29], v[40:41], 0, v[120:121]
	global_load_dwordx4 v[24:27], v[44:45], off offset:128
	s_nop 0
	global_load_dwordx4 v[28:31], v[28:29], off
	s_waitcnt vmcnt(0)
	v_pk_fma_f32 v[22:23], v[22:23], v[30:31], v[26:27]
	v_pk_fma_f32 v[20:21], v[20:21], v[28:29], v[24:25]
	global_store_dwordx4 v[36:37], v[20:23], off offset:128
	v_lshl_add_u64 v[24:25], v[40:41], 0, v[122:123]
	global_load_dwordx4 v[20:23], v[44:45], off offset:192
	s_nop 0
	global_load_dwordx4 v[24:27], v[24:25], off
	s_waitcnt vmcnt(0)
	v_pk_fma_f32 v[18:19], v[18:19], v[26:27], v[22:23]
	v_pk_fma_f32 v[16:17], v[16:17], v[24:25], v[20:21]
	global_store_dwordx4 v[36:37], v[16:19], off offset:192
	s_nop 1
	v_or_b32_e32 v16, 0x70, v124
	v_ashrrev_i32_e32 v17, 31, v16
	v_lshl_add_u64 v[16:17], s[86:87], 0, v[16:17]
	v_alignbit_b32 v18, v17, v16, 13
	v_add_u32_e32 v18, s10, v18
	v_mad_i64_i32 v[18:19], s[24:25], v18, s33, v[126:127]
	v_lshlrev_b64 v[16:17], 12, v[16:17]
	v_lshl_add_u64 v[24:25], v[18:19], 0, s[84:85]
	v_lshl_add_u64 v[18:19], s[36:37], 0, v[16:17]
	v_lshl_add_u64 v[28:29], v[18:19], 0, v[80:81]
	v_lshl_add_u64 v[20:21], v[24:25], 0, v[80:81]
	v_lshl_add_u64 v[26:27], s[38:39], 0, v[16:17]
	global_load_dwordx4 v[16:19], v[28:29], off
	s_nop 0
	global_load_dwordx4 v[20:23], v[20:21], off
	s_waitcnt vmcnt(0)
	v_pk_fma_f32 v[14:15], v[14:15], v[22:23], v[18:19]
	v_pk_fma_f32 v[12:13], v[12:13], v[20:21], v[16:17]
	v_lshl_add_u64 v[20:21], v[26:27], 0, v[80:81]
	global_store_dwordx4 v[20:21], v[12:15], off
	v_lshl_add_u64 v[16:17], v[24:25], 0, v[118:119]
	global_load_dwordx4 v[12:15], v[28:29], off offset:64
	s_nop 0
	global_load_dwordx4 v[16:19], v[16:17], off
	s_waitcnt vmcnt(0)
	v_pk_fma_f32 v[10:11], v[10:11], v[18:19], v[14:15]
	v_pk_fma_f32 v[8:9], v[8:9], v[16:17], v[12:13]
	global_store_dwordx4 v[20:21], v[8:11], off offset:64
	v_lshl_add_u64 v[12:13], v[24:25], 0, v[120:121]
	global_load_dwordx4 v[8:11], v[28:29], off offset:128
	s_nop 0
	global_load_dwordx4 v[12:15], v[12:13], off
	s_waitcnt vmcnt(0)
	v_pk_fma_f32 v[6:7], v[6:7], v[14:15], v[10:11]
	v_pk_fma_f32 v[4:5], v[4:5], v[12:13], v[8:9]
	global_store_dwordx4 v[20:21], v[4:7], off offset:128
	v_lshl_add_u64 v[8:9], v[24:25], 0, v[122:123]
	global_load_dwordx4 v[4:7], v[28:29], off offset:192
	s_nop 0
	global_load_dwordx4 v[8:11], v[8:9], off
	s_waitcnt vmcnt(0)
	v_pk_fma_f32 v[2:3], v[2:3], v[10:11], v[6:7]
	v_pk_fma_f32 v[0:1], v[0:1], v[8:9], v[4:5]
	global_store_dwordx4 v[20:21], v[0:3], off offset:192
	s_cbranch_scc1 .LBB0_1285
	s_mov_b32 s12, 0x3000000
	s_branch .LBB0_182
